# v45 plus s_nop 0 in front of the five MFMA/DS instructions that no flexible VALU op could re-align (0 misaligned in the attention loop)
# baseline (speedup 1.0000x reference)
; DI void attn_item(const P& p, int l, int item, char* smem) {
;     ...
;   for (int kt = -1; kt < 128; ++kt) {
;     if (kt + 1 < 128) {
;       u16* Kd = Ks + ((kt + 1) & 1) * (256 * 72);
;       u16* Vd = Kd + 2 * 64 * 72;
; #pragma unroll
;       for (int i = 0; i < 2; ++i) {
;         const int row = tid >> 3, kc = tid & 7;
;         *(u32x4*)(Kd + (i * 64 + row) * 72 + kc * 8) = kreg[i];
;       }
; #pragma unroll
;       for (int i = 0; i < 2; ++i) {
;         const int cid = tid + NT * i;
;         const int e = cid >> 3, kc = cid & 7;
;         uint2 w0; w0.x = vreg[i][0]; w0.y = vreg[i][1];
;         uint2 w1; w1.x = vreg[i][2]; w1.y = vreg[i][3];
;         u16* vd = Vd + e * 72 + (kc >> 1) * 16 + (kc & 1) * 4;
;         *(uint2*)vd = w0;
;         *(uint2*)(vd + 8) = w1;
;       }
;     }
;     if (kt + 2 < 128) {
;       const int kn = kt + 2;
; #pragma unroll
;       for (int i = 0; i < 2; ++i) kreg[i] = *(const u32x4*)(kbase + ((size_t)i * SEQ + kn * 64) * 64 + tid * 8);
; #pragma unroll
;       for (int i = 0; i < 2; ++i) {
;         const int cid = tid + NT * i;
;         const int e = cid >> 3, kc = cid & 7;
;         vreg[i] = *(const u32x4*)(vbase + (size_t)e * VTP + kn * 64 + kc * 8);
;       }
;     }
;     __builtin_amdgcn_sched_barrier(0x38F);
;     if (kt >= 0) {
;       const u16* Kc = Ks + (kt & 1) * (256 * 72);
;       const u16* Vc = Kc + 2 * 64 * 72;
;       bf16x8 kf[8];
; #pragma unroll
;       for (int i = 0; i < 8; ++i)
;         kf[i] = *(const bf16x8*)(Kc + (c * 64 + 32 * (i & 1) + li) * 72 + 16 * (i >> 1) + 8 * g);
;       u32x4 vf[16];
; #pragma unroll
;       for (int i = 0; i < 16; ++i) {
;         const int eb = i & 3, s = (i >> 2) & 1, kb = i >> 3;
;         vf[i] = *(const u32x4*)(Vc + (32 * eb + li) * 72 + 32 * kb + 16 * s + 8 * g);
;       }
;       f32x16 S[2];
; #pragma unroll
;       for (int kb = 0; kb < 2; ++kb)
; #pragma unroll
;         for (int r = 0; r < 16; ++r) S[kb][r] = negm;
; #pragma unroll
;       for (int i = 0; i < 8; ++i) S[i & 1] = MFMA(kf[i], qf[i >> 1], S[i & 1]);
;       u32x4 pk[4];
;       float sum = 0.f;
; #pragma unroll
;       for (int ch = 0; ch < 4; ++ch) {
;         const int kb = ch >> 1, s = ch & 1;
; #pragma unroll
;         for (int j2 = 0; j2 < 4; ++j2) {
;           const float p0 = __builtin_amdgcn_exp2f(S[kb][8 * s + 2 * j2]);
.Lat_loop:
	s_waitcnt lgkmcnt(4)
	s_nop 0
	v_mfma_f32_32x32x16_bf16 v[64:79], v[136:139], v[176:179], v[64:79]
	ds_read_b128 v[136:139], v151 offset:9248
	v_exp_f32_e32 v104, v104
	v_exp_f32_e32 v105, v105
	v_mfma_f32_32x32x16_bf16 v[48:63], v[152:155], v[176:179], v[48:63]
	ds_read_b128 v[152:155], v151 offset:13856
	v_exp_f32_e64 v106, v106
	v_exp_f32_e32 v107, v107
	v_cvt_pk_bf16_f32 v180, v104, v105
	s_waitcnt lgkmcnt(4)
	v_mfma_f32_32x32x16_bf16 v[32:47], v[224:227], v[176:179], v[32:47]
	ds_read_b128 v[224:227], v151 offset:64
	v_exp_f32_e32 v108, v108
	v_exp_f32_e32 v109, v109
	v_cvt_pk_bf16_f32 v181, v106, v107
	v_mfma_f32_32x32x16_bf16 v[0:15], v[244:247], v[176:179], v[0:15]
	ds_read_b128 v[244:247], v151 offset:4672
	v_exp_f32_e32 v110, v110
	v_exp_f32_e32 v111, v111
	v_cvt_pk_bf16_f32 v182, v108, v109
	v_cvt_pk_bf16_f32 v183, v110, v111
	s_nop 0
	s_waitcnt lgkmcnt(4)
	v_mfma_f32_32x32x16_bf16 v[64:79], v[128:131], v[180:183], v[64:79]
	ds_read_b128 v[128:131], v151 offset:9280
	v_exp_f32_e32 v80, v80
	v_exp_f32_e32 v81, v81
	v_mfma_f32_32x32x16_bf16 v[48:63], v[132:135], v[180:183], v[48:63]
	ds_read_b128 v[132:135], v151 offset:13888
	v_exp_f32_e64 v82, v82
	v_exp_f32_e32 v83, v83
	v_cvt_pk_bf16_f32 v184, v80, v81
	s_waitcnt lgkmcnt(4)
	v_mfma_f32_32x32x16_bf16 v[32:47], v[136:139], v[180:183], v[32:47]
	ds_read_b128 v[136:139], v151 offset:96
	v_exp_f32_e32 v84, v84
	v_exp_f32_e32 v85, v85
	v_cvt_pk_bf16_f32 v185, v82, v83
	v_mfma_f32_32x32x16_bf16 v[0:15], v[152:155], v[180:183], v[0:15]
	ds_read_b128 v[152:155], v151 offset:4704
	v_exp_f32_e32 v86, v86
	v_exp_f32_e32 v87, v87
	v_cvt_pk_bf16_f32 v186, v84, v85
	v_cvt_pk_bf16_f32 v187, v86, v87
	s_nop 0
	s_waitcnt lgkmcnt(4)
	v_mfma_f32_32x32x16_bf16 v[64:79], v[224:227], v[184:187], v[64:79]
	ds_read_b128 v[224:227], v151 offset:9312
	v_exp_f32_e32 v88, v88
	v_exp_f32_e32 v89, v89
	v_mfma_f32_32x32x16_bf16 v[48:63], v[244:247], v[184:187], v[48:63]
	ds_read_b128 v[244:247], v151 offset:13920
	v_exp_f32_e64 v90, v90
	v_exp_f32_e32 v91, v91
	v_cvt_pk_bf16_f32 v192, v88, v89
	s_waitcnt lgkmcnt(4)
	v_mfma_f32_32x32x16_bf16 v[32:47], v[128:131], v[184:187], v[32:47]
	v_exp_f32_e64 v92, v92
	v_exp_f32_e32 v93, v93
	v_cvt_pk_bf16_f32 v193, v90, v91
	s_waitcnt vmcnt(0)
	ds_write_b128 v168, v[228:231] offset:36864
	ds_write_b128 v168, v[232:235] offset:46080
	v_mfma_f32_32x32x16_bf16 v[0:15], v[132:135], v[184:187], v[0:15]
	v_exp_f32_e64 v94, v94
	v_exp_f32_e32 v95, v95
	v_cvt_pk_bf16_f32 v194, v92, v93
	v_cvt_pk_bf16_f32 v195, v94, v95
	s_nop 0
	ds_write_b64 v169, v[236:237] offset:55296
	ds_write_b64 v169, v[238:239] offset:55312
	s_waitcnt lgkmcnt(6)
	s_nop 0
	v_mfma_f32_32x32x16_bf16 v[64:79], v[136:139], v[192:195], v[64:79]
	v_add_f32_e32 v167, v167, v104
	v_add_f32_e32 v190, v190, v105
	v_add_f32_e32 v191, v191, v106
	v_add_f32_e32 v196, v196, v107
	ds_write_b64 v143, v[240:241] offset:55296
	ds_write_b64 v143, v[242:243] offset:55312
	v_mfma_f32_32x32x16_bf16 v[48:63], v[152:155], v[192:195], v[48:63]
	v_add_f32_e32 v167, v167, v108
	v_add_f32_e32 v190, v190, v109
	v_add_f32_e64 v191, v191, v110
	v_add_f32_e32 v196, v196, v111
	s_waitcnt lgkmcnt(6)
	v_mfma_f32_32x32x16_bf16 v[32:47], v[224:227], v[192:195], v[32:47]
	v_add_f32_e32 v167, v167, v80
	v_add_f32_e32 v190, v190, v81
	v_add_f32_e32 v191, v191, v82
	v_add_f32_e32 v196, v196, v83
	v_mfma_f32_32x32x16_bf16 v[0:15], v[244:247], v[192:195], v[0:15]
	v_add_f32_e32 v167, v167, v84
	v_add_f32_e32 v190, v190, v85
	v_add_f32_e32 v191, v191, v86
	v_add_f32_e32 v196, v196, v87
	s_waitcnt lgkmcnt(0)
	s_barrier
	ds_read_b128 v[128:131], v150 offset:36864
	ds_read_b128 v[132:135], v150 offset:36896
	ds_read_b128 v[136:139], v150 offset:36928
	ds_read_b128 v[152:155], v150 offset:36960
	ds_read_b128 v[224:227], v150 offset:41472
	ds_read_b128 v[244:247], v150 offset:41504
	global_load_dwordx4 v[232:235], v148, s[98:99]
	global_load_dwordx4 v[228:231], v156, s[98:99]
	global_load_dwordx4 v[236:239], v146, s[100:101]
	global_load_dwordx4 v[240:243], v144, s[100:101]
	s_waitcnt lgkmcnt(4)
	s_nop 0
	v_mfma_f32_32x32x16_bf16 v[96:111], v[128:131], v[112:115], v[16:31]
	ds_read_b128 v[128:131], v150 offset:41536
	v_add_f32_e32 v167, v167, v88
	v_add_f32_e32 v190, v190, v89
	v_mfma_f32_32x32x16_bf16 v[96:111], v[132:135], v[116:119], v[96:111]
	ds_read_b128 v[132:135], v150 offset:41568
	v_add_f32_e64 v191, v191, v90
	v_add_f32_e32 v196, v196, v91
	s_waitcnt lgkmcnt(4)
	v_mfma_f32_32x32x16_bf16 v[96:111], v[136:139], v[124:127], v[96:111]
	ds_read_b128 v[136:139], v151 offset:36864
	v_add_f32_e32 v167, v167, v92
	v_add_f32_e32 v190, v190, v93
	v_mfma_f32_32x32x16_bf16 v[96:111], v[152:155], v[120:123], v[96:111]
	ds_read_b128 v[152:155], v151 offset:41472
	v_add_f32_e64 v191, v191, v94
	v_add_f32_e32 v196, v196, v95
	s_add_u32 s98, s98, s14
	s_addc_u32 s99, s99, s15
	s_waitcnt lgkmcnt(4)
	v_mfma_f32_32x32x16_bf16 v[80:95], v[224:227], v[112:115], v[16:31]
	ds_read_b128 v[224:227], v151 offset:46080
	s_add_u32 s100, s100, s58
	s_addc_u32 s101, s101, s59
	v_mfma_f32_32x32x16_bf16 v[80:95], v[244:247], v[116:119], v[80:95]
	ds_read_b128 v[244:247], v151 offset:50688
	s_nop 2
	v_exp_f32_e32 v96, v96
	v_exp_f32_e32 v97, v97
	s_waitcnt lgkmcnt(4)
	v_mfma_f32_32x32x16_bf16 v[80:95], v[128:131], v[124:127], v[80:95]
	ds_read_b128 v[128:131], v151 offset:36896
	v_exp_f32_e32 v98, v98
	v_exp_f32_e32 v99, v99
	v_exp_f32_e64 v100, v100
	v_mfma_f32_32x32x16_bf16 v[80:95], v[132:135], v[120:123], v[80:95]
	ds_read_b128 v[132:135], v151 offset:41504
	v_exp_f32_e32 v101, v101
	v_exp_f32_e32 v102, v102
	v_exp_f32_e32 v103, v103
	v_add_f32_e32 v167, v167, v96
	v_add_f32_e32 v190, v190, v97
	v_add_f32_e32 v191, v191, v98
	v_cvt_pk_bf16_f32 v176, v96, v97
	v_cvt_pk_bf16_f32 v177, v98, v99
	v_cvt_pk_bf16_f32 v178, v100, v101
	v_cvt_pk_bf16_f32 v179, v102, v103
	v_add_f32_e32 v196, v196, v99
	v_add_f32_e32 v167, v167, v100
	v_add_f32_e32 v190, v190, v101
	v_add_f32_e32 v191, v191, v102
	v_add_f32_e32 v196, v196, v103
	s_waitcnt lgkmcnt(4)
; DI void attn_item(const P& p, int l, int item, char* smem) {
;     ...
;   for (int kt = -1; kt < 128; ++kt) {
;     if (kt + 1 < 128) {
;       u16* Kd = Ks + ((kt + 1) & 1) * (256 * 72);
;       u16* Vd = Kd + 2 * 64 * 72;
; #pragma unroll
;       for (int i = 0; i < 2; ++i) {
;         const int row = tid >> 3, kc = tid & 7;
;         *(u32x4*)(Kd + (i * 64 + row) * 72 + kc * 8) = kreg[i];
;       }
; #pragma unroll
;       for (int i = 0; i < 2; ++i) {
;         const int cid = tid + NT * i;
;         const int e = cid >> 3, kc = cid & 7;
;         uint2 w0; w0.x = vreg[i][0]; w0.y = vreg[i][1];
;         uint2 w1; w1.x = vreg[i][2]; w1.y = vreg[i][3];
;         u16* vd = Vd + e * 72 + (kc >> 1) * 16 + (kc & 1) * 4;
;         *(uint2*)vd = w0;
;         *(uint2*)(vd + 8) = w1;
;       }
;     }
;     if (kt + 2 < 128) {
;       const int kn = kt + 2;
; #pragma unroll
;       for (int i = 0; i < 2; ++i) kreg[i] = *(const u32x4*)(kbase + ((size_t)i * SEQ + kn * 64) * 64 + tid * 8);
; #pragma unroll
;       for (int i = 0; i < 2; ++i) {
;         const int cid = tid + NT * i;
;         const int e = cid >> 3, kc = cid & 7;
;         vreg[i] = *(const u32x4*)(vbase + (size_t)e * VTP + kn * 64 + kc * 8);
;       }
;     }
;     __builtin_amdgcn_sched_barrier(0x38F);
;     if (kt >= 0) {
;       const u16* Kc = Ks + (kt & 1) * (256 * 72);
;       const u16* Vc = Kc + 2 * 64 * 72;
;       bf16x8 kf[8];
; #pragma unroll
;       for (int i = 0; i < 8; ++i)
;         kf[i] = *(const bf16x8*)(Kc + (c * 64 + 32 * (i & 1) + li) * 72 + 16 * (i >> 1) + 8 * g);
;       u32x4 vf[16];
; #pragma unroll
;       for (int i = 0; i < 16; ++i) {
;         const int eb = i & 3, s = (i >> 2) & 1, kb = i >> 3;
;         vf[i] = *(const u32x4*)(Vc + (32 * eb + li) * 72 + 32 * kb + 16 * s + 8 * g);
;       }
;       f32x16 S[2];
; #pragma unroll
;       for (int kb = 0; kb < 2; ++kb)
; #pragma unroll
;         for (int r = 0; r < 16; ++r) S[kb][r] = negm;
; #pragma unroll
;       for (int i = 0; i < 8; ++i) S[i & 1] = MFMA(kf[i], qf[i >> 1], S[i & 1]);
;       u32x4 pk[4];
;       float sum = 0.f;
; #pragma unroll
;       for (int ch = 0; ch < 4; ++ch) {
;         const int kb = ch >> 1, s = ch & 1;
; #pragma unroll
;         for (int j2 = 0; j2 < 4; ++j2) {
;           const float p0 = __builtin_amdgcn_exp2f(S[kb][8 * s + 2 * j2]);
	v_mfma_f32_32x32x16_bf16 v[64:79], v[136:139], v[176:179], v[64:79]
	ds_read_b128 v[136:139], v151 offset:46112
	v_exp_f32_e32 v104, v104
	v_exp_f32_e32 v105, v105
	v_mfma_f32_32x32x16_bf16 v[48:63], v[152:155], v[176:179], v[48:63]
	ds_read_b128 v[152:155], v151 offset:50720
	v_exp_f32_e64 v106, v106
	v_exp_f32_e32 v107, v107
	v_cvt_pk_bf16_f32 v180, v104, v105
	s_waitcnt lgkmcnt(4)
	v_mfma_f32_32x32x16_bf16 v[32:47], v[224:227], v[176:179], v[32:47]
	ds_read_b128 v[224:227], v151 offset:36928
	v_exp_f32_e32 v108, v108
	v_exp_f32_e32 v109, v109
	v_cvt_pk_bf16_f32 v181, v106, v107
	v_mfma_f32_32x32x16_bf16 v[0:15], v[244:247], v[176:179], v[0:15]
	ds_read_b128 v[244:247], v151 offset:41536
	v_exp_f32_e32 v110, v110
	v_exp_f32_e32 v111, v111
	v_cvt_pk_bf16_f32 v182, v108, v109
	v_cvt_pk_bf16_f32 v183, v110, v111
	s_nop 0
	s_waitcnt lgkmcnt(4)
	v_mfma_f32_32x32x16_bf16 v[64:79], v[128:131], v[180:183], v[64:79]
	ds_read_b128 v[128:131], v151 offset:46144
	v_exp_f32_e32 v80, v80
	v_exp_f32_e32 v81, v81
	v_mfma_f32_32x32x16_bf16 v[48:63], v[132:135], v[180:183], v[48:63]
	ds_read_b128 v[132:135], v151 offset:50752
	v_exp_f32_e64 v82, v82
	v_exp_f32_e32 v83, v83
	v_cvt_pk_bf16_f32 v184, v80, v81
	s_waitcnt lgkmcnt(4)
	v_mfma_f32_32x32x16_bf16 v[32:47], v[136:139], v[180:183], v[32:47]
	ds_read_b128 v[136:139], v151 offset:36960
	v_exp_f32_e32 v84, v84
	v_exp_f32_e32 v85, v85
	v_cvt_pk_bf16_f32 v185, v82, v83
	v_mfma_f32_32x32x16_bf16 v[0:15], v[152:155], v[180:183], v[0:15]
	ds_read_b128 v[152:155], v151 offset:41568
	v_exp_f32_e32 v86, v86
	v_exp_f32_e32 v87, v87
	v_cvt_pk_bf16_f32 v186, v84, v85
	v_cvt_pk_bf16_f32 v187, v86, v87
	s_nop 0
	s_waitcnt lgkmcnt(4)
	v_mfma_f32_32x32x16_bf16 v[64:79], v[224:227], v[184:187], v[64:79]
	ds_read_b128 v[224:227], v151 offset:46176
	v_exp_f32_e32 v88, v88
	v_exp_f32_e32 v89, v89
	v_mfma_f32_32x32x16_bf16 v[48:63], v[244:247], v[184:187], v[48:63]
	ds_read_b128 v[244:247], v151 offset:50784
	v_exp_f32_e64 v90, v90
	v_exp_f32_e32 v91, v91
	v_cvt_pk_bf16_f32 v192, v88, v89
	s_waitcnt lgkmcnt(4)
	v_mfma_f32_32x32x16_bf16 v[32:47], v[128:131], v[184:187], v[32:47]
	v_exp_f32_e64 v92, v92
	v_exp_f32_e32 v93, v93
	v_cvt_pk_bf16_f32 v193, v90, v91
	s_waitcnt vmcnt(0)
	ds_write_b128 v168, v[228:231] offset:0
	ds_write_b128 v168, v[232:235] offset:9216
	v_mfma_f32_32x32x16_bf16 v[0:15], v[132:135], v[184:187], v[0:15]
	v_exp_f32_e64 v94, v94
	v_exp_f32_e32 v95, v95
	v_cvt_pk_bf16_f32 v194, v92, v93
	v_cvt_pk_bf16_f32 v195, v94, v95
	s_nop 0
	ds_write_b64 v169, v[236:237] offset:18432
	ds_write_b64 v169, v[238:239] offset:18448
	s_waitcnt lgkmcnt(6)
	s_nop 0
	v_mfma_f32_32x32x16_bf16 v[64:79], v[136:139], v[192:195], v[64:79]
	v_add_f32_e32 v167, v167, v104
	v_add_f32_e32 v190, v190, v105
	v_add_f32_e32 v191, v191, v106
	v_add_f32_e32 v196, v196, v107
	ds_write_b64 v143, v[240:241] offset:18432
	ds_write_b64 v143, v[242:243] offset:18448
	v_mfma_f32_32x32x16_bf16 v[48:63], v[152:155], v[192:195], v[48:63]
	v_add_f32_e32 v167, v167, v108
	v_add_f32_e32 v190, v190, v109
	v_add_f32_e64 v191, v191, v110
	v_add_f32_e32 v196, v196, v111
	s_waitcnt lgkmcnt(6)
	v_mfma_f32_32x32x16_bf16 v[32:47], v[224:227], v[192:195], v[32:47]
	v_add_f32_e32 v167, v167, v80
	v_add_f32_e32 v190, v190, v81
	v_add_f32_e32 v191, v191, v82
	v_add_f32_e32 v196, v196, v83
	v_mfma_f32_32x32x16_bf16 v[0:15], v[244:247], v[192:195], v[0:15]
	v_add_f32_e32 v167, v167, v84
	v_add_f32_e32 v190, v190, v85
	v_add_f32_e64 v191, v191, v86
	v_add_f32_e32 v196, v196, v87
	s_waitcnt lgkmcnt(0)
	s_barrier
	s_add_i32 s10, s10, -1
	s_cmp_eq_u32 s10, 0
	s_cbranch_scc1 .Lat_exit
	ds_read_b128 v[128:131], v150 offset:0
	ds_read_b128 v[132:135], v150 offset:32
	ds_read_b128 v[136:139], v150 offset:64
	ds_read_b128 v[152:155], v150 offset:96
	ds_read_b128 v[224:227], v150 offset:4608
	ds_read_b128 v[244:247], v150 offset:4640
	global_load_dwordx4 v[232:235], v148, s[98:99]
	global_load_dwordx4 v[228:231], v156, s[98:99]
	global_load_dwordx4 v[236:239], v146, s[100:101]
	global_load_dwordx4 v[240:243], v144, s[100:101]
	s_waitcnt lgkmcnt(4)
	s_nop 0
	v_mfma_f32_32x32x16_bf16 v[96:111], v[128:131], v[112:115], v[16:31]
	ds_read_b128 v[128:131], v150 offset:4672
	v_add_f32_e32 v167, v167, v88
	v_add_f32_e32 v190, v190, v89
	v_mfma_f32_32x32x16_bf16 v[96:111], v[132:135], v[116:119], v[96:111]
	ds_read_b128 v[132:135], v150 offset:4704
	v_add_f32_e64 v191, v191, v90
	v_add_f32_e32 v196, v196, v91
	s_waitcnt lgkmcnt(4)
	v_mfma_f32_32x32x16_bf16 v[96:111], v[136:139], v[124:127], v[96:111]
	ds_read_b128 v[136:139], v151 offset:0
	v_add_f32_e32 v167, v167, v92
	v_add_f32_e32 v190, v190, v93
	v_mfma_f32_32x32x16_bf16 v[96:111], v[152:155], v[120:123], v[96:111]
	ds_read_b128 v[152:155], v151 offset:4608
	v_add_f32_e64 v191, v191, v94
	v_add_f32_e32 v196, v196, v95
	s_add_u32 s98, s98, s14
	s_addc_u32 s99, s99, s15
	s_waitcnt lgkmcnt(4)
	v_mfma_f32_32x32x16_bf16 v[80:95], v[224:227], v[112:115], v[16:31]
	ds_read_b128 v[224:227], v151 offset:9216
	s_add_u32 s100, s100, s58
	s_addc_u32 s101, s101, s59
	v_mfma_f32_32x32x16_bf16 v[80:95], v[244:247], v[116:119], v[80:95]
	ds_read_b128 v[244:247], v151 offset:13824
	s_nop 2
	v_exp_f32_e32 v96, v96
	v_exp_f32_e32 v97, v97
	s_waitcnt lgkmcnt(4)
	v_mfma_f32_32x32x16_bf16 v[80:95], v[128:131], v[124:127], v[80:95]
	ds_read_b128 v[128:131], v151 offset:32
	v_exp_f32_e32 v98, v98
	v_exp_f32_e32 v99, v99
	v_exp_f32_e64 v100, v100
	v_mfma_f32_32x32x16_bf16 v[80:95], v[132:135], v[120:123], v[80:95]
	ds_read_b128 v[132:135], v151 offset:4640
	v_exp_f32_e32 v101, v101
	v_exp_f32_e32 v102, v102
	v_exp_f32_e32 v103, v103
	v_add_f32_e32 v167, v167, v96
	v_add_f32_e32 v190, v190, v97
	v_add_f32_e32 v191, v191, v98
	v_cvt_pk_bf16_f32 v176, v96, v97
	v_cvt_pk_bf16_f32 v177, v98, v99
	v_cvt_pk_bf16_f32 v178, v100, v101
	v_cvt_pk_bf16_f32 v179, v102, v103
	v_add_f32_e32 v196, v196, v99
	v_add_f32_e32 v167, v167, v100
	v_add_f32_e32 v190, v190, v101
	v_add_f32_e32 v191, v191, v102
	v_add_f32_e64 v196, v196, v103
	s_branch .Lat_loop
